# grid barrier: last cross-XCD leader releases all per-XCD generation words itself (one hop less) and every workgroup issues its L1 invalidate at arrival instead of after release; on top of the combined
# speedup vs baseline: 1.0229x; 1.0031x over previous
; __device__ __forceinline__ unsigned xb_ld(unsigned* p)              { return __hip_atomic_load(p, __ATOMIC_RELAXED, __HIP_MEMORY_SCOPE_AGENT); }
; __device__ __forceinline__ unsigned xb_add(unsigned* p, unsigned v) { return __hip_atomic_fetch_add(p, v, __ATOMIC_RELAXED, __HIP_MEMORY_SCOPE_AGENT); }
; #define XB_SPIN(cond, bar) do { unsigned _sp = 0; while (cond) { __builtin_amdgcn_s_sleep(1); \
;     if ((++_sp & 255u) == 0u) { if (xb_ld(&(bar)[XB_TMO])) break; if (_sp > XB_SPIN_CAP) { atomicAdd(&(bar)[XB_TMO], 1u); break; } } } } while (0)
; __device__ __forceinline__ void xcd_barrier(const XcdBarrier& b, int xtid) {
;     ...
;         const unsigned old = xb_add(&bar[XB_XSUB(b.x)], 1u);
;         const unsigned gen = old / nloc;
;         if (old + 1u == (gen + 1u) * nloc) {
;             __builtin_amdgcn_fence(__ATOMIC_RELEASE, "agent");
;             asm volatile("s_waitcnt vmcnt(0)" ::: "memory");
;             const unsigned og = xb_add(&bar[XB_TOP], 1u);
;             const unsigned tg = og / nx;
;             if (og + 1u == (tg + 1u) * nx) xb_add(&bar[XB_TOPGEN], 1u);
;             else XB_SPIN(xb_ld(&bar[XB_TOPGEN]) == tg, bar);
;             __builtin_amdgcn_fence(__ATOMIC_ACQUIRE, "agent");
;             xb_add(&bar[XB_XGEN(b.x)], 1u);
;             asm volatile("s_waitcnt vmcnt(0)" ::: "memory");
;         } else {
;             XB_SPIN(xb_ld(&bar[XB_XGEN(b.x)]) == gen, bar);
.LBB0_123:
	s_or_b64 exec, exec, s[8:9]
	v_cvt_f32_u32_e32 v4, v2
	s_waitcnt vmcnt(0)
	v_readfirstlane_b32 s6, v3
	v_sub_u32_e32 v3, 0, v2
	v_rcp_iflag_f32_e32 v4, v4
	v_add_u32_e32 v5, s6, v1
	v_mul_f32_e32 v4, 0x4f7ffffe, v4
	v_cvt_u32_f32_e32 v4, v4
	v_mul_lo_u32 v1, v3, v4
	v_mul_hi_u32 v1, v4, v1
	v_add_u32_e32 v1, v4, v1
	v_mul_hi_u32 v1, v5, v1
	v_mul_lo_u32 v3, v1, v2
	v_sub_u32_e32 v3, v5, v3
	v_add_u32_e32 v4, 1, v1
	v_cmp_ge_u32_e32 vcc, v3, v2
	s_nop 1
	v_cndmask_b32_e32 v1, v1, v4, vcc
	v_sub_u32_e32 v4, v3, v2
	v_cndmask_b32_e32 v3, v3, v4, vcc
	v_add_u32_e32 v4, 1, v1
	v_cmp_ge_u32_e32 vcc, v3, v2
	v_add_u32_e32 v3, 1, v5
	s_nop 0
	v_cndmask_b32_e32 v1, v1, v4, vcc
	v_mul_lo_u32 v4, v2, v1
	v_add_u32_e32 v2, v4, v2
	v_cmp_ne_u32_e32 vcc, v3, v2
	s_and_saveexec_b64 s[6:7], vcc
	s_xor_b64 s[6:7], exec, s[6:7]
	s_cbranch_execz .LBB0_137
	s_waitcnt lgkmcnt(0)
	buffer_inv sc1
	global_load_dword v0, v201, s[4:5] offset:1024 sc1
	s_add_u32 s10, s4, 0x2400
	s_addc_u32 s11, s5, 0
	s_waitcnt vmcnt(0)
	v_cmp_eq_u32_e32 vcc, v0, v1
	s_and_saveexec_b64 s[8:9], vcc
	s_cbranch_execz .LBB0_136
	s_mov_b32 s22, 1
	s_mov_b64 s[12:13], 0
	s_branch .LBB0_127

; __device__ __forceinline__ unsigned xb_ld(unsigned* p)              { return __hip_atomic_load(p, __ATOMIC_RELAXED, __HIP_MEMORY_SCOPE_AGENT); }
; __device__ __forceinline__ unsigned xb_add(unsigned* p, unsigned v) { return __hip_atomic_fetch_add(p, v, __ATOMIC_RELAXED, __HIP_MEMORY_SCOPE_AGENT); }
; #define XB_SPIN(cond, bar) do { unsigned _sp = 0; while (cond) { __builtin_amdgcn_s_sleep(1); \
;     if ((++_sp & 255u) == 0u) { if (xb_ld(&(bar)[XB_TMO])) break; if (_sp > XB_SPIN_CAP) { atomicAdd(&(bar)[XB_TMO], 1u); break; } } } } while (0)
; __device__ __forceinline__ void xcd_barrier(const XcdBarrier& b, int xtid) {
;     ...
;         const unsigned old = xb_add(&bar[XB_XSUB(b.x)], 1u);
;         const unsigned gen = old / nloc;
;         if (old + 1u == (gen + 1u) * nloc) {
;             __builtin_amdgcn_fence(__ATOMIC_RELEASE, "agent");
;             asm volatile("s_waitcnt vmcnt(0)" ::: "memory");
;             const unsigned og = xb_add(&bar[XB_TOP], 1u);
;             const unsigned tg = og / nx;
;             if (og + 1u == (tg + 1u) * nx) xb_add(&bar[XB_TOPGEN], 1u);
;             else XB_SPIN(xb_ld(&bar[XB_TOPGEN]) == tg, bar);
;             __builtin_amdgcn_fence(__ATOMIC_ACQUIRE, "agent");
;             xb_add(&bar[XB_XGEN(b.x)], 1u);
;             asm volatile("s_waitcnt vmcnt(0)" ::: "memory");
;         } else {
;             XB_SPIN(xb_ld(&bar[XB_XGEN(b.x)]) == gen, bar);
.LBB0_136:
	s_or_b64 exec, exec, s[8:9]
	s_waitcnt vmcnt(0)
	s_nop 0
	s_waitcnt vmcnt(0)
.LBB0_137:
	s_andn2_saveexec_b64 s[6:7], s[6:7]
	s_cbranch_execz .LBB0_157
	s_mov_b64 s[6:7], exec
	buffer_inv sc1
	buffer_wbl2 sc1
	s_waitcnt lgkmcnt(0)
	s_waitcnt vmcnt(0)
	v_mbcnt_lo_u32_b32 v1, s6, 0
	v_mbcnt_hi_u32_b32 v1, s7, v1
	v_cmp_eq_u32_e32 vcc, 0, v1
	s_and_saveexec_b64 s[8:9], vcc
	s_cbranch_execz .LBB0_140
	s_bcnt1_i32_b64 s6, s[6:7]
	v_mov_b32_e32 v2, s6
	v_readlane_b32 s6, v253, 14
	v_readlane_b32 s7, v253, 15
	s_nop 4
	global_atomic_add v2, v161, v2, s[6:7] sc0
.LBB0_140:
	s_or_b64 exec, exec, s[8:9]
	s_waitcnt vmcnt(0)
	v_readfirstlane_b32 s6, v2
	v_cvt_f32_u32_e32 v2, v0
	v_sub_u32_e32 v3, 0, v0
	v_add_u32_e32 v1, s6, v1
	v_readlane_b32 s6, v253, 16
	v_rcp_iflag_f32_e32 v2, v2
	v_readlane_b32 s7, v253, 17
	s_mov_b64 s[8:9], -1
	v_mul_f32_e32 v2, 0x4f7ffffe, v2
	v_cvt_u32_f32_e32 v2, v2
	v_mul_lo_u32 v3, v3, v2
	v_mul_hi_u32 v3, v2, v3
	v_add_u32_e32 v2, v2, v3
	v_mul_hi_u32 v2, v1, v2
	v_mul_lo_u32 v3, v2, v0
	v_sub_u32_e32 v3, v1, v3
	v_cmp_ge_u32_e32 vcc, v3, v0
	v_add_u32_e32 v4, 1, v2
	v_add_u32_e32 v1, 1, v1
	v_cndmask_b32_e32 v2, v2, v4, vcc
	v_sub_u32_e32 v4, v3, v0
	v_cndmask_b32_e32 v3, v3, v4, vcc
	v_cmp_ge_u32_e32 vcc, v3, v0
	v_add_u32_e32 v3, 1, v2
	s_nop 0
	v_cndmask_b32_e32 v2, v2, v3, vcc
	v_mul_lo_u32 v3, v0, v2
	v_add_u32_e32 v0, v3, v0
	v_cmp_ne_u32_e32 vcc, v1, v0
	v_mov_b64_e32 v[0:1], s[6:7]
	s_and_saveexec_b64 s[6:7], vcc
	s_cbranch_execnz .Lxs_nl_12
	s_mov_b64 exec, s[6:7]
	v_readlane_b32 s98, v252, 37
	v_readlane_b32 s99, v252, 38
	v_mov_b32_e32 v3, 1
	s_nop 1
	s_add_u32 s98, s98, 0x2400
	s_addc_u32 s99, s99, 0
	s_nop 4
	global_atomic_add v161, v3, s[98:99]
	global_atomic_add v161, v3, s[98:99] offset:256
	global_atomic_add v161, v3, s[98:99] offset:512
	global_atomic_add v161, v3, s[98:99] offset:768
	global_atomic_add v161, v3, s[98:99] offset:1024
	global_atomic_add v161, v3, s[98:99] offset:1280
	global_atomic_add v161, v3, s[98:99] offset:1536
	global_atomic_add v161, v3, s[98:99] offset:1792
	global_atomic_add v161, v3, s[98:99] offset:2048
	global_atomic_add v161, v3, s[98:99] offset:2304
	global_atomic_add v161, v3, s[98:99] offset:2560
	global_atomic_add v161, v3, s[98:99] offset:2816
	global_atomic_add v161, v3, s[98:99] offset:3072
	global_atomic_add v161, v3, s[98:99] offset:3328
	global_atomic_add v161, v3, s[98:99] offset:3584
	global_atomic_add v161, v3, s[98:99] offset:3840
	s_branch .LBB0_152
.Lxs_nl_12:
	v_readlane_b32 s8, v253, 16
	v_readlane_b32 s9, v253, 17
	s_mov_b64 s[10:11], 0
	s_nop 3
	global_load_dword v0, v161, s[8:9] sc1
	s_waitcnt vmcnt(0)
	v_cmp_eq_u32_e32 vcc, v0, v2
	s_and_saveexec_b64 s[8:9], vcc
	s_cbranch_execz .LBB0_151
	s_mov_b32 s20, 1
	s_branch .LBB0_144

; __device__ __forceinline__ unsigned xb_ld(unsigned* p)              { return __hip_atomic_load(p, __ATOMIC_RELAXED, __HIP_MEMORY_SCOPE_AGENT); }
; __device__ __forceinline__ unsigned xb_add(unsigned* p, unsigned v) { return __hip_atomic_fetch_add(p, v, __ATOMIC_RELAXED, __HIP_MEMORY_SCOPE_AGENT); }
; #define XB_SPIN(cond, bar) do { unsigned _sp = 0; while (cond) { __builtin_amdgcn_s_sleep(1); \
;     if ((++_sp & 255u) == 0u) { if (xb_ld(&(bar)[XB_TMO])) break; if (_sp > XB_SPIN_CAP) { atomicAdd(&(bar)[XB_TMO], 1u); break; } } } } while (0)
; __device__ __forceinline__ void xcd_barrier(const XcdBarrier& b, int xtid) {
;     ...
;             if (og + 1u == (tg + 1u) * nx) xb_add(&bar[XB_TOPGEN], 1u);
;             else XB_SPIN(xb_ld(&bar[XB_TOPGEN]) == tg, bar);
;             __builtin_amdgcn_fence(__ATOMIC_ACQUIRE, "agent");
;             xb_add(&bar[XB_XGEN(b.x)], 1u);
;             asm volatile("s_waitcnt vmcnt(0)" ::: "memory");
.LBB0_154:
	s_or_b64 exec, exec, s[6:7]
	s_mov_b64 s[6:7], exec
	v_mbcnt_lo_u32_b32 v0, s6, 0
	v_mbcnt_hi_u32_b32 v0, s7, v0
	v_cmp_eq_u32_e32 vcc, 0, v0
	s_waitcnt vmcnt(0)
	s_nop 0
	s_and_saveexec_b64 s[8:9], vcc
	s_cbranch_execz .LBB0_156
	s_bcnt1_i32_b64 s6, s[6:7]
	v_mov_b32_e32 v0, s6
	s_nop 0

; __device__ __forceinline__ unsigned xb_ld(unsigned* p)              { return __hip_atomic_load(p, __ATOMIC_RELAXED, __HIP_MEMORY_SCOPE_AGENT); }
; __device__ __forceinline__ unsigned xb_add(unsigned* p, unsigned v) { return __hip_atomic_fetch_add(p, v, __ATOMIC_RELAXED, __HIP_MEMORY_SCOPE_AGENT); }
; #define XB_SPIN(cond, bar) do { unsigned _sp = 0; while (cond) { __builtin_amdgcn_s_sleep(1); \
;     if ((++_sp & 255u) == 0u) { if (xb_ld(&(bar)[XB_TMO])) break; if (_sp > XB_SPIN_CAP) { atomicAdd(&(bar)[XB_TMO], 1u); break; } } } } while (0)
; __device__ __forceinline__ void xcd_barrier(const XcdBarrier& b, int xtid) {
;     ...
;         const unsigned old = xb_add(&bar[XB_XSUB(b.x)], 1u);
;         const unsigned gen = old / nloc;
;         if (old + 1u == (gen + 1u) * nloc) {
;             __builtin_amdgcn_fence(__ATOMIC_RELEASE, "agent");
;             asm volatile("s_waitcnt vmcnt(0)" ::: "memory");
;             const unsigned og = xb_add(&bar[XB_TOP], 1u);
;             const unsigned tg = og / nx;
;             if (og + 1u == (tg + 1u) * nx) xb_add(&bar[XB_TOPGEN], 1u);
;             else XB_SPIN(xb_ld(&bar[XB_TOPGEN]) == tg, bar);
;             __builtin_amdgcn_fence(__ATOMIC_ACQUIRE, "agent");
;             xb_add(&bar[XB_XGEN(b.x)], 1u);
;             asm volatile("s_waitcnt vmcnt(0)" ::: "memory");
;         } else {
;             XB_SPIN(xb_ld(&bar[XB_XGEN(b.x)]) == gen, bar);
.LBB0_241:
	s_or_b64 exec, exec, s[10:11]
	v_cvt_f32_u32_e32 v4, v2
	s_waitcnt vmcnt(0)
	v_readfirstlane_b32 s8, v3
	v_sub_u32_e32 v3, 0, v2
	v_rcp_iflag_f32_e32 v4, v4
	v_add_u32_e32 v5, s8, v1
	v_mul_f32_e32 v4, 0x4f7ffffe, v4
	v_cvt_u32_f32_e32 v4, v4
	v_mul_lo_u32 v1, v3, v4
	v_mul_hi_u32 v1, v4, v1
	v_add_u32_e32 v1, v4, v1
	v_mul_hi_u32 v1, v5, v1
	v_mul_lo_u32 v3, v1, v2
	v_sub_u32_e32 v3, v5, v3
	v_add_u32_e32 v4, 1, v1
	v_cmp_ge_u32_e32 vcc, v3, v2
	s_nop 1
	v_cndmask_b32_e32 v1, v1, v4, vcc
	v_sub_u32_e32 v4, v3, v2
	v_cndmask_b32_e32 v3, v3, v4, vcc
	v_add_u32_e32 v4, 1, v1
	v_cmp_ge_u32_e32 vcc, v3, v2
	v_add_u32_e32 v3, 1, v5
	s_nop 0
	v_cndmask_b32_e32 v1, v1, v4, vcc
	v_mul_lo_u32 v4, v2, v1
	v_add_u32_e32 v2, v4, v2
	v_cmp_ne_u32_e32 vcc, v3, v2
	s_and_saveexec_b64 s[8:9], vcc
	s_xor_b64 s[8:9], exec, s[8:9]
	s_cbranch_execz .LBB0_255
	s_waitcnt lgkmcnt(0)
	buffer_inv sc1
	global_load_dword v0, v201, s[6:7] offset:1024 sc1
	s_add_u32 s12, s6, 0x2400
	s_addc_u32 s13, s7, 0
	s_waitcnt vmcnt(0)
	v_cmp_eq_u32_e32 vcc, v0, v1
	s_and_saveexec_b64 s[10:11], vcc
	s_cbranch_execz .LBB0_254
	s_mov_b32 s24, 1
	s_mov_b64 s[14:15], 0
	s_branch .LBB0_245

; __device__ __forceinline__ unsigned xb_ld(unsigned* p)              { return __hip_atomic_load(p, __ATOMIC_RELAXED, __HIP_MEMORY_SCOPE_AGENT); }
; __device__ __forceinline__ unsigned xb_add(unsigned* p, unsigned v) { return __hip_atomic_fetch_add(p, v, __ATOMIC_RELAXED, __HIP_MEMORY_SCOPE_AGENT); }
; #define XB_SPIN(cond, bar) do { unsigned _sp = 0; while (cond) { __builtin_amdgcn_s_sleep(1); \
;     if ((++_sp & 255u) == 0u) { if (xb_ld(&(bar)[XB_TMO])) break; if (_sp > XB_SPIN_CAP) { atomicAdd(&(bar)[XB_TMO], 1u); break; } } } } while (0)
; __device__ __forceinline__ void xcd_barrier(const XcdBarrier& b, int xtid) {
;     ...
;         const unsigned old = xb_add(&bar[XB_XSUB(b.x)], 1u);
;         const unsigned gen = old / nloc;
;         if (old + 1u == (gen + 1u) * nloc) {
;             __builtin_amdgcn_fence(__ATOMIC_RELEASE, "agent");
;             asm volatile("s_waitcnt vmcnt(0)" ::: "memory");
;             const unsigned og = xb_add(&bar[XB_TOP], 1u);
;             const unsigned tg = og / nx;
;             if (og + 1u == (tg + 1u) * nx) xb_add(&bar[XB_TOPGEN], 1u);
;             else XB_SPIN(xb_ld(&bar[XB_TOPGEN]) == tg, bar);
;             __builtin_amdgcn_fence(__ATOMIC_ACQUIRE, "agent");
;             xb_add(&bar[XB_XGEN(b.x)], 1u);
;             asm volatile("s_waitcnt vmcnt(0)" ::: "memory");
;         } else {
;             XB_SPIN(xb_ld(&bar[XB_XGEN(b.x)]) == gen, bar);
.LBB0_254:
	s_or_b64 exec, exec, s[10:11]
	s_waitcnt vmcnt(0)
	s_nop 0
	s_waitcnt vmcnt(0)
.LBB0_255:
	s_andn2_saveexec_b64 s[8:9], s[8:9]
	s_cbranch_execz .LBB0_275
	s_mov_b64 s[8:9], exec
	buffer_inv sc1
	buffer_wbl2 sc1
	s_waitcnt lgkmcnt(0)
	s_waitcnt vmcnt(0)
	v_mbcnt_lo_u32_b32 v1, s8, 0
	v_mbcnt_hi_u32_b32 v1, s9, v1
	v_cmp_eq_u32_e32 vcc, 0, v1
	s_and_saveexec_b64 s[10:11], vcc
	s_cbranch_execz .LBB0_258
	s_bcnt1_i32_b64 s8, s[8:9]
	v_mov_b32_e32 v2, s8
	v_readlane_b32 s8, v253, 14
	v_readlane_b32 s9, v253, 15
	s_nop 4
	global_atomic_add v2, v161, v2, s[8:9] sc0
.LBB0_258:
	s_or_b64 exec, exec, s[10:11]
	s_waitcnt vmcnt(0)
	v_readfirstlane_b32 s8, v2
	v_cvt_f32_u32_e32 v2, v0
	v_sub_u32_e32 v3, 0, v0
	v_add_u32_e32 v1, s8, v1
	v_readlane_b32 s8, v253, 16
	v_rcp_iflag_f32_e32 v2, v2
	v_readlane_b32 s9, v253, 17
	s_mov_b64 s[10:11], -1
	v_mul_f32_e32 v2, 0x4f7ffffe, v2
	v_cvt_u32_f32_e32 v2, v2
	v_mul_lo_u32 v3, v3, v2
	v_mul_hi_u32 v3, v2, v3
	v_add_u32_e32 v2, v2, v3
	v_mul_hi_u32 v2, v1, v2
	v_mul_lo_u32 v3, v2, v0
	v_sub_u32_e32 v3, v1, v3
	v_cmp_ge_u32_e32 vcc, v3, v0
	v_add_u32_e32 v4, 1, v2
	v_add_u32_e32 v1, 1, v1
	v_cndmask_b32_e32 v2, v2, v4, vcc
	v_sub_u32_e32 v4, v3, v0
	v_cndmask_b32_e32 v3, v3, v4, vcc
	v_cmp_ge_u32_e32 vcc, v3, v0
	v_add_u32_e32 v3, 1, v2
	s_nop 0
	v_cndmask_b32_e32 v2, v2, v3, vcc
	v_mul_lo_u32 v3, v0, v2
	v_add_u32_e32 v0, v3, v0
	v_cmp_ne_u32_e32 vcc, v1, v0
	v_mov_b64_e32 v[0:1], s[8:9]
	s_and_saveexec_b64 s[8:9], vcc
	s_cbranch_execnz .Lxs_nl_11
	s_mov_b64 exec, s[8:9]
	v_readlane_b32 s98, v252, 37
	v_readlane_b32 s99, v252, 38
	v_mov_b32_e32 v3, 1
	s_nop 1
	s_add_u32 s98, s98, 0x2400
	s_addc_u32 s99, s99, 0
	s_nop 4
	global_atomic_add v161, v3, s[98:99]
	global_atomic_add v161, v3, s[98:99] offset:256
	global_atomic_add v161, v3, s[98:99] offset:512
	global_atomic_add v161, v3, s[98:99] offset:768
	global_atomic_add v161, v3, s[98:99] offset:1024
	global_atomic_add v161, v3, s[98:99] offset:1280
	global_atomic_add v161, v3, s[98:99] offset:1536
	global_atomic_add v161, v3, s[98:99] offset:1792
	global_atomic_add v161, v3, s[98:99] offset:2048
	global_atomic_add v161, v3, s[98:99] offset:2304
	global_atomic_add v161, v3, s[98:99] offset:2560
	global_atomic_add v161, v3, s[98:99] offset:2816
	global_atomic_add v161, v3, s[98:99] offset:3072
	global_atomic_add v161, v3, s[98:99] offset:3328
	global_atomic_add v161, v3, s[98:99] offset:3584
	global_atomic_add v161, v3, s[98:99] offset:3840
	s_branch .LBB0_270
.Lxs_nl_11:
	v_readlane_b32 s10, v253, 16
	v_readlane_b32 s11, v253, 17
	s_mov_b64 s[12:13], 0
	s_nop 3
	global_load_dword v0, v161, s[10:11] sc1
	s_waitcnt vmcnt(0)
	v_cmp_eq_u32_e32 vcc, v0, v2
	s_and_saveexec_b64 s[10:11], vcc
	s_cbranch_execz .LBB0_269
	s_mov_b32 s22, 1
	s_branch .LBB0_262

; __device__ __forceinline__ unsigned xb_ld(unsigned* p)              { return __hip_atomic_load(p, __ATOMIC_RELAXED, __HIP_MEMORY_SCOPE_AGENT); }
; __device__ __forceinline__ unsigned xb_add(unsigned* p, unsigned v) { return __hip_atomic_fetch_add(p, v, __ATOMIC_RELAXED, __HIP_MEMORY_SCOPE_AGENT); }
; #define XB_SPIN(cond, bar) do { unsigned _sp = 0; while (cond) { __builtin_amdgcn_s_sleep(1); \
;     if ((++_sp & 255u) == 0u) { if (xb_ld(&(bar)[XB_TMO])) break; if (_sp > XB_SPIN_CAP) { atomicAdd(&(bar)[XB_TMO], 1u); break; } } } } while (0)
; __device__ __forceinline__ void xcd_barrier(const XcdBarrier& b, int xtid) {
;     ...
;             if (og + 1u == (tg + 1u) * nx) xb_add(&bar[XB_TOPGEN], 1u);
;             else XB_SPIN(xb_ld(&bar[XB_TOPGEN]) == tg, bar);
;             __builtin_amdgcn_fence(__ATOMIC_ACQUIRE, "agent");
;             xb_add(&bar[XB_XGEN(b.x)], 1u);
;             asm volatile("s_waitcnt vmcnt(0)" ::: "memory");
.LBB0_272:
	s_or_b64 exec, exec, s[8:9]
	s_mov_b64 s[8:9], exec
	v_mbcnt_lo_u32_b32 v0, s8, 0
	v_mbcnt_hi_u32_b32 v0, s9, v0
	v_cmp_eq_u32_e32 vcc, 0, v0
	s_waitcnt vmcnt(0)
	s_nop 0
	s_and_saveexec_b64 s[10:11], vcc
	s_cbranch_execz .LBB0_274
	s_bcnt1_i32_b64 s8, s[8:9]
	v_mov_b32_e32 v0, s8
	s_nop 0

; __device__ __forceinline__ unsigned xb_ld(unsigned* p)              { return __hip_atomic_load(p, __ATOMIC_RELAXED, __HIP_MEMORY_SCOPE_AGENT); }
; __device__ __forceinline__ unsigned xb_add(unsigned* p, unsigned v) { return __hip_atomic_fetch_add(p, v, __ATOMIC_RELAXED, __HIP_MEMORY_SCOPE_AGENT); }
; #define XB_SPIN(cond, bar) do { unsigned _sp = 0; while (cond) { __builtin_amdgcn_s_sleep(1); \
;     if ((++_sp & 255u) == 0u) { if (xb_ld(&(bar)[XB_TMO])) break; if (_sp > XB_SPIN_CAP) { atomicAdd(&(bar)[XB_TMO], 1u); break; } } } } while (0)
; __device__ __forceinline__ void xcd_barrier(const XcdBarrier& b, int xtid) {
;     ...
;         const unsigned old = xb_add(&bar[XB_XSUB(b.x)], 1u);
;         const unsigned gen = old / nloc;
;         if (old + 1u == (gen + 1u) * nloc) {
;             __builtin_amdgcn_fence(__ATOMIC_RELEASE, "agent");
;             asm volatile("s_waitcnt vmcnt(0)" ::: "memory");
;             const unsigned og = xb_add(&bar[XB_TOP], 1u);
;             const unsigned tg = og / nx;
;             if (og + 1u == (tg + 1u) * nx) xb_add(&bar[XB_TOPGEN], 1u);
;             else XB_SPIN(xb_ld(&bar[XB_TOPGEN]) == tg, bar);
;             __builtin_amdgcn_fence(__ATOMIC_ACQUIRE, "agent");
;             xb_add(&bar[XB_XGEN(b.x)], 1u);
;             asm volatile("s_waitcnt vmcnt(0)" ::: "memory");
;         } else {
;             XB_SPIN(xb_ld(&bar[XB_XGEN(b.x)]) == gen, bar);
.LBB0_444:
	s_or_b64 exec, exec, s[12:13]
	v_cvt_f32_u32_e32 v4, v2
	s_waitcnt vmcnt(0)
	v_readfirstlane_b32 s10, v3
	v_sub_u32_e32 v3, 0, v2
	v_rcp_iflag_f32_e32 v4, v4
	v_add_u32_e32 v5, s10, v1
	v_mul_f32_e32 v4, 0x4f7ffffe, v4
	v_cvt_u32_f32_e32 v4, v4
	v_mul_lo_u32 v1, v3, v4
	v_mul_hi_u32 v1, v4, v1
	v_add_u32_e32 v1, v4, v1
	v_mul_hi_u32 v1, v5, v1
	v_mul_lo_u32 v3, v1, v2
	v_sub_u32_e32 v3, v5, v3
	v_add_u32_e32 v4, 1, v1
	v_cmp_ge_u32_e32 vcc, v3, v2
	s_nop 1
	v_cndmask_b32_e32 v1, v1, v4, vcc
	v_sub_u32_e32 v4, v3, v2
	v_cndmask_b32_e32 v3, v3, v4, vcc
	v_add_u32_e32 v4, 1, v1
	v_cmp_ge_u32_e32 vcc, v3, v2
	v_add_u32_e32 v3, 1, v5
	s_nop 0
	v_cndmask_b32_e32 v1, v1, v4, vcc
	v_mul_lo_u32 v4, v2, v1
	v_add_u32_e32 v2, v4, v2
	v_cmp_ne_u32_e32 vcc, v3, v2
	s_and_saveexec_b64 s[10:11], vcc
	s_xor_b64 s[10:11], exec, s[10:11]
	s_cbranch_execz .LBB0_458
	s_waitcnt lgkmcnt(0)
	buffer_inv sc1
	global_load_dword v0, v201, s[8:9] offset:1024 sc1
	s_add_u32 s14, s8, 0x2400
	s_addc_u32 s15, s9, 0
	s_waitcnt vmcnt(0)
	v_cmp_eq_u32_e32 vcc, v0, v1
	s_and_saveexec_b64 s[12:13], vcc
	s_cbranch_execz .LBB0_457
	s_mov_b32 s26, 1
	s_mov_b64 s[16:17], 0
	s_branch .LBB0_448

; __device__ __forceinline__ unsigned xb_ld(unsigned* p)              { return __hip_atomic_load(p, __ATOMIC_RELAXED, __HIP_MEMORY_SCOPE_AGENT); }
; __device__ __forceinline__ unsigned xb_add(unsigned* p, unsigned v) { return __hip_atomic_fetch_add(p, v, __ATOMIC_RELAXED, __HIP_MEMORY_SCOPE_AGENT); }
; #define XB_SPIN(cond, bar) do { unsigned _sp = 0; while (cond) { __builtin_amdgcn_s_sleep(1); \
;     if ((++_sp & 255u) == 0u) { if (xb_ld(&(bar)[XB_TMO])) break; if (_sp > XB_SPIN_CAP) { atomicAdd(&(bar)[XB_TMO], 1u); break; } } } } while (0)
; __device__ __forceinline__ void xcd_barrier(const XcdBarrier& b, int xtid) {
;     ...
;         const unsigned old = xb_add(&bar[XB_XSUB(b.x)], 1u);
;         const unsigned gen = old / nloc;
;         if (old + 1u == (gen + 1u) * nloc) {
;             __builtin_amdgcn_fence(__ATOMIC_RELEASE, "agent");
;             asm volatile("s_waitcnt vmcnt(0)" ::: "memory");
;             const unsigned og = xb_add(&bar[XB_TOP], 1u);
;             const unsigned tg = og / nx;
;             if (og + 1u == (tg + 1u) * nx) xb_add(&bar[XB_TOPGEN], 1u);
;             else XB_SPIN(xb_ld(&bar[XB_TOPGEN]) == tg, bar);
;             __builtin_amdgcn_fence(__ATOMIC_ACQUIRE, "agent");
;             xb_add(&bar[XB_XGEN(b.x)], 1u);
;             asm volatile("s_waitcnt vmcnt(0)" ::: "memory");
;         } else {
;             XB_SPIN(xb_ld(&bar[XB_XGEN(b.x)]) == gen, bar);
.LBB0_457:
	s_or_b64 exec, exec, s[12:13]
	s_waitcnt vmcnt(0)
	s_nop 0
	s_waitcnt vmcnt(0)
.LBB0_458:
	s_andn2_saveexec_b64 s[10:11], s[10:11]
	s_cbranch_execz .LBB0_478
	s_mov_b64 s[10:11], exec
	buffer_inv sc1
	buffer_wbl2 sc1
	s_waitcnt lgkmcnt(0)
	s_waitcnt vmcnt(0)
	v_mbcnt_lo_u32_b32 v1, s10, 0
	v_mbcnt_hi_u32_b32 v1, s11, v1
	v_cmp_eq_u32_e32 vcc, 0, v1
	s_and_saveexec_b64 s[12:13], vcc
	s_cbranch_execz .LBB0_461
	s_bcnt1_i32_b64 s10, s[10:11]
	v_mov_b32_e32 v2, s10
	v_readlane_b32 s10, v253, 14
	v_readlane_b32 s11, v253, 15
	s_nop 4
	global_atomic_add v2, v161, v2, s[10:11] sc0
.LBB0_461:
	s_or_b64 exec, exec, s[12:13]
	s_waitcnt vmcnt(0)
	v_readfirstlane_b32 s10, v2
	v_cvt_f32_u32_e32 v2, v0
	v_sub_u32_e32 v3, 0, v0
	v_add_u32_e32 v1, s10, v1
	v_readlane_b32 s10, v253, 16
	v_rcp_iflag_f32_e32 v2, v2
	v_readlane_b32 s11, v253, 17
	s_mov_b64 s[12:13], -1
	v_mul_f32_e32 v2, 0x4f7ffffe, v2
	v_cvt_u32_f32_e32 v2, v2
	v_mul_lo_u32 v3, v3, v2
	v_mul_hi_u32 v3, v2, v3
	v_add_u32_e32 v2, v2, v3
	v_mul_hi_u32 v2, v1, v2
	v_mul_lo_u32 v3, v2, v0
	v_sub_u32_e32 v3, v1, v3
	v_cmp_ge_u32_e32 vcc, v3, v0
	v_add_u32_e32 v4, 1, v2
	v_add_u32_e32 v1, 1, v1
	v_cndmask_b32_e32 v2, v2, v4, vcc
	v_sub_u32_e32 v4, v3, v0
	v_cndmask_b32_e32 v3, v3, v4, vcc
	v_cmp_ge_u32_e32 vcc, v3, v0
	v_add_u32_e32 v3, 1, v2
	s_nop 0
	v_cndmask_b32_e32 v2, v2, v3, vcc
	v_mul_lo_u32 v3, v0, v2
	v_add_u32_e32 v0, v3, v0
	v_cmp_ne_u32_e32 vcc, v1, v0
	v_mov_b64_e32 v[0:1], s[10:11]
	s_and_saveexec_b64 s[10:11], vcc
	s_cbranch_execnz .Lxs_nl_8
	s_mov_b64 exec, s[10:11]
	v_readlane_b32 s98, v252, 37
	v_readlane_b32 s99, v252, 38
	v_mov_b32_e32 v3, 1
	s_nop 1
	s_add_u32 s98, s98, 0x2400
	s_addc_u32 s99, s99, 0
	s_nop 4
	global_atomic_add v161, v3, s[98:99]
	global_atomic_add v161, v3, s[98:99] offset:256
	global_atomic_add v161, v3, s[98:99] offset:512
	global_atomic_add v161, v3, s[98:99] offset:768
	global_atomic_add v161, v3, s[98:99] offset:1024
	global_atomic_add v161, v3, s[98:99] offset:1280
	global_atomic_add v161, v3, s[98:99] offset:1536
	global_atomic_add v161, v3, s[98:99] offset:1792
	global_atomic_add v161, v3, s[98:99] offset:2048
	global_atomic_add v161, v3, s[98:99] offset:2304
	global_atomic_add v161, v3, s[98:99] offset:2560
	global_atomic_add v161, v3, s[98:99] offset:2816
	global_atomic_add v161, v3, s[98:99] offset:3072
	global_atomic_add v161, v3, s[98:99] offset:3328
	global_atomic_add v161, v3, s[98:99] offset:3584
	global_atomic_add v161, v3, s[98:99] offset:3840
	s_branch .LBB0_473
.Lxs_nl_8:
	v_readlane_b32 s12, v253, 16
	v_readlane_b32 s13, v253, 17
	s_mov_b64 s[14:15], 0
	s_nop 3
	global_load_dword v0, v161, s[12:13] sc1
	s_waitcnt vmcnt(0)
	v_cmp_eq_u32_e32 vcc, v0, v2
	s_and_saveexec_b64 s[12:13], vcc
	s_cbranch_execz .LBB0_472
	s_mov_b32 s24, 1
	s_branch .LBB0_465

; __device__ __forceinline__ unsigned xb_ld(unsigned* p)              { return __hip_atomic_load(p, __ATOMIC_RELAXED, __HIP_MEMORY_SCOPE_AGENT); }
; __device__ __forceinline__ unsigned xb_add(unsigned* p, unsigned v) { return __hip_atomic_fetch_add(p, v, __ATOMIC_RELAXED, __HIP_MEMORY_SCOPE_AGENT); }
; #define XB_SPIN(cond, bar) do { unsigned _sp = 0; while (cond) { __builtin_amdgcn_s_sleep(1); \
;     if ((++_sp & 255u) == 0u) { if (xb_ld(&(bar)[XB_TMO])) break; if (_sp > XB_SPIN_CAP) { atomicAdd(&(bar)[XB_TMO], 1u); break; } } } } while (0)
; __device__ __forceinline__ void xcd_barrier(const XcdBarrier& b, int xtid) {
;     ...
;             if (og + 1u == (tg + 1u) * nx) xb_add(&bar[XB_TOPGEN], 1u);
;             else XB_SPIN(xb_ld(&bar[XB_TOPGEN]) == tg, bar);
;             __builtin_amdgcn_fence(__ATOMIC_ACQUIRE, "agent");
;             xb_add(&bar[XB_XGEN(b.x)], 1u);
;             asm volatile("s_waitcnt vmcnt(0)" ::: "memory");
.LBB0_475:
	s_or_b64 exec, exec, s[10:11]
	s_mov_b64 s[10:11], exec
	v_mbcnt_lo_u32_b32 v0, s10, 0
	v_mbcnt_hi_u32_b32 v0, s11, v0
	v_cmp_eq_u32_e32 vcc, 0, v0
	s_waitcnt vmcnt(0)
	s_nop 0
	s_and_saveexec_b64 s[12:13], vcc
	s_cbranch_execz .LBB0_477
	s_bcnt1_i32_b64 s10, s[10:11]
	v_mov_b32_e32 v0, s10
	s_nop 0

; __device__ __forceinline__ unsigned xb_ld(unsigned* p)              { return __hip_atomic_load(p, __ATOMIC_RELAXED, __HIP_MEMORY_SCOPE_AGENT); }
; __device__ __forceinline__ unsigned xb_add(unsigned* p, unsigned v) { return __hip_atomic_fetch_add(p, v, __ATOMIC_RELAXED, __HIP_MEMORY_SCOPE_AGENT); }
; #define XB_SPIN(cond, bar) do { unsigned _sp = 0; while (cond) { __builtin_amdgcn_s_sleep(1); \
;     if ((++_sp & 255u) == 0u) { if (xb_ld(&(bar)[XB_TMO])) break; if (_sp > XB_SPIN_CAP) { atomicAdd(&(bar)[XB_TMO], 1u); break; } } } } while (0)
; __device__ __forceinline__ void xcd_barrier(const XcdBarrier& b, int xtid) {
;     ...
;         const unsigned old = xb_add(&bar[XB_XSUB(b.x)], 1u);
;         const unsigned gen = old / nloc;
;         if (old + 1u == (gen + 1u) * nloc) {
;             __builtin_amdgcn_fence(__ATOMIC_RELEASE, "agent");
;             asm volatile("s_waitcnt vmcnt(0)" ::: "memory");
;             const unsigned og = xb_add(&bar[XB_TOP], 1u);
;             const unsigned tg = og / nx;
;             if (og + 1u == (tg + 1u) * nx) xb_add(&bar[XB_TOPGEN], 1u);
;             else XB_SPIN(xb_ld(&bar[XB_TOPGEN]) == tg, bar);
;             __builtin_amdgcn_fence(__ATOMIC_ACQUIRE, "agent");
;             xb_add(&bar[XB_XGEN(b.x)], 1u);
;             asm volatile("s_waitcnt vmcnt(0)" ::: "memory");
;         } else {
;             XB_SPIN(xb_ld(&bar[XB_XGEN(b.x)]) == gen, bar);
.LBB0_510:
	s_or_b64 exec, exec, s[14:15]
	v_cvt_f32_u32_e32 v4, v2
	s_waitcnt vmcnt(0)
	v_readfirstlane_b32 s12, v3
	v_sub_u32_e32 v3, 0, v2
	v_rcp_iflag_f32_e32 v4, v4
	v_add_u32_e32 v5, s12, v1
	v_mul_f32_e32 v4, 0x4f7ffffe, v4
	v_cvt_u32_f32_e32 v4, v4
	v_mul_lo_u32 v1, v3, v4
	v_mul_hi_u32 v1, v4, v1
	v_add_u32_e32 v1, v4, v1
	v_mul_hi_u32 v1, v5, v1
	v_mul_lo_u32 v3, v1, v2
	v_sub_u32_e32 v3, v5, v3
	v_add_u32_e32 v4, 1, v1
	v_cmp_ge_u32_e32 vcc, v3, v2
	s_nop 1
	v_cndmask_b32_e32 v1, v1, v4, vcc
	v_sub_u32_e32 v4, v3, v2
	v_cndmask_b32_e32 v3, v3, v4, vcc
	v_add_u32_e32 v4, 1, v1
	v_cmp_ge_u32_e32 vcc, v3, v2
	v_add_u32_e32 v3, 1, v5
	s_nop 0
	v_cndmask_b32_e32 v1, v1, v4, vcc
	v_mul_lo_u32 v4, v2, v1
	v_add_u32_e32 v2, v4, v2
	v_cmp_ne_u32_e32 vcc, v3, v2
	s_and_saveexec_b64 s[12:13], vcc
	s_xor_b64 s[12:13], exec, s[12:13]
	s_cbranch_execz .LBB0_524
	s_waitcnt lgkmcnt(0)
	buffer_inv sc1
	global_load_dword v0, v201, s[8:9] offset:1024 sc1
	s_add_u32 s16, s8, 0x2400
	s_addc_u32 s17, s9, 0
	s_waitcnt vmcnt(0)
	v_cmp_eq_u32_e32 vcc, v0, v1
	s_and_saveexec_b64 s[14:15], vcc
	s_cbranch_execz .LBB0_523
	s_mov_b32 s28, 1
	s_mov_b64 s[18:19], 0
	s_branch .LBB0_514

; __device__ __forceinline__ unsigned xb_ld(unsigned* p)              { return __hip_atomic_load(p, __ATOMIC_RELAXED, __HIP_MEMORY_SCOPE_AGENT); }
; __device__ __forceinline__ unsigned xb_add(unsigned* p, unsigned v) { return __hip_atomic_fetch_add(p, v, __ATOMIC_RELAXED, __HIP_MEMORY_SCOPE_AGENT); }
; #define XB_SPIN(cond, bar) do { unsigned _sp = 0; while (cond) { __builtin_amdgcn_s_sleep(1); \
;     if ((++_sp & 255u) == 0u) { if (xb_ld(&(bar)[XB_TMO])) break; if (_sp > XB_SPIN_CAP) { atomicAdd(&(bar)[XB_TMO], 1u); break; } } } } while (0)
; __device__ __forceinline__ void xcd_barrier(const XcdBarrier& b, int xtid) {
;     ...
;         const unsigned old = xb_add(&bar[XB_XSUB(b.x)], 1u);
;         const unsigned gen = old / nloc;
;         if (old + 1u == (gen + 1u) * nloc) {
;             __builtin_amdgcn_fence(__ATOMIC_RELEASE, "agent");
;             asm volatile("s_waitcnt vmcnt(0)" ::: "memory");
;             const unsigned og = xb_add(&bar[XB_TOP], 1u);
;             const unsigned tg = og / nx;
;             if (og + 1u == (tg + 1u) * nx) xb_add(&bar[XB_TOPGEN], 1u);
;             else XB_SPIN(xb_ld(&bar[XB_TOPGEN]) == tg, bar);
;             __builtin_amdgcn_fence(__ATOMIC_ACQUIRE, "agent");
;             xb_add(&bar[XB_XGEN(b.x)], 1u);
;             asm volatile("s_waitcnt vmcnt(0)" ::: "memory");
;         } else {
;             XB_SPIN(xb_ld(&bar[XB_XGEN(b.x)]) == gen, bar);
.LBB0_523:
	s_or_b64 exec, exec, s[14:15]
	s_waitcnt vmcnt(0)
	s_nop 0
	s_waitcnt vmcnt(0)
.LBB0_524:
	s_andn2_saveexec_b64 s[12:13], s[12:13]
	s_cbranch_execz .LBB0_544
	s_mov_b64 s[12:13], exec
	buffer_inv sc1
	buffer_wbl2 sc1
	s_waitcnt lgkmcnt(0)
	s_waitcnt vmcnt(0)
	v_mbcnt_lo_u32_b32 v1, s12, 0
	v_mbcnt_hi_u32_b32 v1, s13, v1
	v_cmp_eq_u32_e32 vcc, 0, v1
	s_and_saveexec_b64 s[14:15], vcc
	s_cbranch_execz .LBB0_527
	s_bcnt1_i32_b64 s12, s[12:13]
	v_mov_b32_e32 v2, s12
	v_readlane_b32 s12, v253, 14
	v_readlane_b32 s13, v253, 15
	s_nop 4
	global_atomic_add v2, v161, v2, s[12:13] sc0
.LBB0_527:
	s_or_b64 exec, exec, s[14:15]
	s_waitcnt vmcnt(0)
	v_readfirstlane_b32 s12, v2
	v_cvt_f32_u32_e32 v2, v0
	v_sub_u32_e32 v3, 0, v0
	v_add_u32_e32 v1, s12, v1
	v_readlane_b32 s12, v253, 16
	v_rcp_iflag_f32_e32 v2, v2
	v_readlane_b32 s13, v253, 17
	s_mov_b64 s[14:15], -1
	v_mul_f32_e32 v2, 0x4f7ffffe, v2
	v_cvt_u32_f32_e32 v2, v2
	v_mul_lo_u32 v3, v3, v2
	v_mul_hi_u32 v3, v2, v3
	v_add_u32_e32 v2, v2, v3
	v_mul_hi_u32 v2, v1, v2
	v_mul_lo_u32 v3, v2, v0
	v_sub_u32_e32 v3, v1, v3
	v_cmp_ge_u32_e32 vcc, v3, v0
	v_add_u32_e32 v4, 1, v2
	v_add_u32_e32 v1, 1, v1
	v_cndmask_b32_e32 v2, v2, v4, vcc
	v_sub_u32_e32 v4, v3, v0
	v_cndmask_b32_e32 v3, v3, v4, vcc
	v_cmp_ge_u32_e32 vcc, v3, v0
	v_add_u32_e32 v3, 1, v2
	s_nop 0
	v_cndmask_b32_e32 v2, v2, v3, vcc
	v_mul_lo_u32 v3, v0, v2
	v_add_u32_e32 v0, v3, v0
	v_cmp_ne_u32_e32 vcc, v1, v0
	v_mov_b64_e32 v[0:1], s[12:13]
	s_and_saveexec_b64 s[12:13], vcc
	s_cbranch_execnz .Lxs_nl_7
	s_mov_b64 exec, s[12:13]
	v_readlane_b32 s98, v252, 37
	v_readlane_b32 s99, v252, 38
	v_mov_b32_e32 v3, 1
	s_nop 1
	s_add_u32 s98, s98, 0x2400
	s_addc_u32 s99, s99, 0
	s_nop 4
	global_atomic_add v161, v3, s[98:99]
	global_atomic_add v161, v3, s[98:99] offset:256
	global_atomic_add v161, v3, s[98:99] offset:512
	global_atomic_add v161, v3, s[98:99] offset:768
	global_atomic_add v161, v3, s[98:99] offset:1024
	global_atomic_add v161, v3, s[98:99] offset:1280
	global_atomic_add v161, v3, s[98:99] offset:1536
	global_atomic_add v161, v3, s[98:99] offset:1792
	global_atomic_add v161, v3, s[98:99] offset:2048
	global_atomic_add v161, v3, s[98:99] offset:2304
	global_atomic_add v161, v3, s[98:99] offset:2560
	global_atomic_add v161, v3, s[98:99] offset:2816
	global_atomic_add v161, v3, s[98:99] offset:3072
	global_atomic_add v161, v3, s[98:99] offset:3328
	global_atomic_add v161, v3, s[98:99] offset:3584
	global_atomic_add v161, v3, s[98:99] offset:3840
	s_branch .LBB0_539
.Lxs_nl_7:
	v_readlane_b32 s14, v253, 16
	v_readlane_b32 s15, v253, 17
	s_mov_b64 s[16:17], 0
	s_nop 3
	global_load_dword v0, v161, s[14:15] sc1
	s_waitcnt vmcnt(0)
	v_cmp_eq_u32_e32 vcc, v0, v2
	s_and_saveexec_b64 s[14:15], vcc
	s_cbranch_execz .LBB0_538
	s_mov_b32 s26, 1
	s_branch .LBB0_531

; __device__ __forceinline__ unsigned xb_ld(unsigned* p)              { return __hip_atomic_load(p, __ATOMIC_RELAXED, __HIP_MEMORY_SCOPE_AGENT); }
; __device__ __forceinline__ unsigned xb_add(unsigned* p, unsigned v) { return __hip_atomic_fetch_add(p, v, __ATOMIC_RELAXED, __HIP_MEMORY_SCOPE_AGENT); }
; #define XB_SPIN(cond, bar) do { unsigned _sp = 0; while (cond) { __builtin_amdgcn_s_sleep(1); \
;     if ((++_sp & 255u) == 0u) { if (xb_ld(&(bar)[XB_TMO])) break; if (_sp > XB_SPIN_CAP) { atomicAdd(&(bar)[XB_TMO], 1u); break; } } } } while (0)
; __device__ __forceinline__ void xcd_barrier(const XcdBarrier& b, int xtid) {
;     ...
;             if (og + 1u == (tg + 1u) * nx) xb_add(&bar[XB_TOPGEN], 1u);
;             else XB_SPIN(xb_ld(&bar[XB_TOPGEN]) == tg, bar);
;             __builtin_amdgcn_fence(__ATOMIC_ACQUIRE, "agent");
;             xb_add(&bar[XB_XGEN(b.x)], 1u);
;             asm volatile("s_waitcnt vmcnt(0)" ::: "memory");
.LBB0_541:
	s_or_b64 exec, exec, s[12:13]
	s_mov_b64 s[12:13], exec
	v_mbcnt_lo_u32_b32 v0, s12, 0
	v_mbcnt_hi_u32_b32 v0, s13, v0
	v_cmp_eq_u32_e32 vcc, 0, v0
	s_waitcnt vmcnt(0)
	s_nop 0
	s_and_saveexec_b64 s[14:15], vcc
	s_cbranch_execz .LBB0_543
	s_bcnt1_i32_b64 s12, s[12:13]
	v_mov_b32_e32 v0, s12
	s_nop 0

; __device__ __forceinline__ unsigned xb_ld(unsigned* p)              { return __hip_atomic_load(p, __ATOMIC_RELAXED, __HIP_MEMORY_SCOPE_AGENT); }
; __device__ __forceinline__ unsigned xb_add(unsigned* p, unsigned v) { return __hip_atomic_fetch_add(p, v, __ATOMIC_RELAXED, __HIP_MEMORY_SCOPE_AGENT); }
; #define XB_SPIN(cond, bar) do { unsigned _sp = 0; while (cond) { __builtin_amdgcn_s_sleep(1); \
;     if ((++_sp & 255u) == 0u) { if (xb_ld(&(bar)[XB_TMO])) break; if (_sp > XB_SPIN_CAP) { atomicAdd(&(bar)[XB_TMO], 1u); break; } } } } while (0)
; __device__ __forceinline__ void xcd_barrier(const XcdBarrier& b, int xtid) {
;     ...
;         const unsigned old = xb_add(&bar[XB_XSUB(b.x)], 1u);
;         const unsigned gen = old / nloc;
;         if (old + 1u == (gen + 1u) * nloc) {
;             __builtin_amdgcn_fence(__ATOMIC_RELEASE, "agent");
;             asm volatile("s_waitcnt vmcnt(0)" ::: "memory");
;             const unsigned og = xb_add(&bar[XB_TOP], 1u);
;             const unsigned tg = og / nx;
;             if (og + 1u == (tg + 1u) * nx) xb_add(&bar[XB_TOPGEN], 1u);
;             else XB_SPIN(xb_ld(&bar[XB_TOPGEN]) == tg, bar);
;             __builtin_amdgcn_fence(__ATOMIC_ACQUIRE, "agent");
;             xb_add(&bar[XB_XGEN(b.x)], 1u);
;             asm volatile("s_waitcnt vmcnt(0)" ::: "memory");
;         } else {
;             XB_SPIN(xb_ld(&bar[XB_XGEN(b.x)]) == gen, bar);
.LBB0_965:
	s_or_b64 exec, exec, s[8:9]
	v_cvt_f32_u32_e32 v4, v2
	s_waitcnt vmcnt(0)
	v_readfirstlane_b32 s6, v3
	v_sub_u32_e32 v3, 0, v2
	v_rcp_iflag_f32_e32 v4, v4
	v_add_u32_e32 v5, s6, v1
	v_mul_f32_e32 v4, 0x4f7ffffe, v4
	v_cvt_u32_f32_e32 v4, v4
	v_mul_lo_u32 v1, v3, v4
	v_mul_hi_u32 v1, v4, v1
	v_add_u32_e32 v1, v4, v1
	v_mul_hi_u32 v1, v5, v1
	v_mul_lo_u32 v3, v1, v2
	v_sub_u32_e32 v3, v5, v3
	v_add_u32_e32 v4, 1, v1
	v_cmp_ge_u32_e32 vcc, v3, v2
	s_nop 1
	v_cndmask_b32_e32 v1, v1, v4, vcc
	v_sub_u32_e32 v4, v3, v2
	v_cndmask_b32_e32 v3, v3, v4, vcc
	v_add_u32_e32 v4, 1, v1
	v_cmp_ge_u32_e32 vcc, v3, v2
	v_add_u32_e32 v3, 1, v5
	s_nop 0
	v_cndmask_b32_e32 v1, v1, v4, vcc
	v_mul_lo_u32 v4, v2, v1
	v_add_u32_e32 v2, v4, v2
	v_cmp_ne_u32_e32 vcc, v3, v2
	s_and_saveexec_b64 s[6:7], vcc
	s_xor_b64 s[6:7], exec, s[6:7]
	s_cbranch_execz .LBB0_979
	s_waitcnt lgkmcnt(0)
	buffer_inv sc1
	global_load_dword v0, v201, s[4:5] offset:1024 sc1
	s_add_u32 s12, s4, 0x2400
	s_addc_u32 s13, s5, 0
	s_waitcnt vmcnt(0)
	v_cmp_eq_u32_e32 vcc, v0, v1
	s_and_saveexec_b64 s[8:9], vcc
	s_cbranch_execz .LBB0_978
	s_mov_b32 s24, 1
	s_mov_b64 s[14:15], 0
	s_branch .LBB0_969

; __device__ __forceinline__ unsigned xb_ld(unsigned* p)              { return __hip_atomic_load(p, __ATOMIC_RELAXED, __HIP_MEMORY_SCOPE_AGENT); }
; __device__ __forceinline__ unsigned xb_add(unsigned* p, unsigned v) { return __hip_atomic_fetch_add(p, v, __ATOMIC_RELAXED, __HIP_MEMORY_SCOPE_AGENT); }
; #define XB_SPIN(cond, bar) do { unsigned _sp = 0; while (cond) { __builtin_amdgcn_s_sleep(1); \
;     if ((++_sp & 255u) == 0u) { if (xb_ld(&(bar)[XB_TMO])) break; if (_sp > XB_SPIN_CAP) { atomicAdd(&(bar)[XB_TMO], 1u); break; } } } } while (0)
; __device__ __forceinline__ void xcd_barrier(const XcdBarrier& b, int xtid) {
;     ...
;             const unsigned og = xb_add(&bar[XB_TOP], 1u);
;             const unsigned tg = og / nx;
;             if (og + 1u == (tg + 1u) * nx) xb_add(&bar[XB_TOPGEN], 1u);
;             else XB_SPIN(xb_ld(&bar[XB_TOPGEN]) == tg, bar);
.Lxs_nl_1:
	v_readlane_b32 s8, v253, 16
	v_readlane_b32 s9, v253, 17
	s_mov_b64 s[12:13], 0
	s_nop 3
	global_load_dword v0, v161, s[8:9] sc1
	s_waitcnt vmcnt(0)
	v_cmp_eq_u32_e32 vcc, v0, v2
	s_and_saveexec_b64 s[8:9], vcc
	s_cbranch_execz .LBB0_993
	s_mov_b32 s22, 1
	s_branch .LBB0_986

; __device__ __forceinline__ unsigned xb_add(unsigned* p, unsigned v) { return __hip_atomic_fetch_add(p, v, __ATOMIC_RELAXED, __HIP_MEMORY_SCOPE_AGENT); }
; __device__ __forceinline__ void xcd_barrier(const XcdBarrier& b, int xtid) {
;     ...
;         if (old + 1u == (gen + 1u) * nloc) {
;             __builtin_amdgcn_fence(__ATOMIC_RELEASE, "agent");
;             asm volatile("s_waitcnt vmcnt(0)" ::: "memory");
;             const unsigned og = xb_add(&bar[XB_TOP], 1u);
.LBB0_1092:
	s_mov_b64 s[6:7], exec
	buffer_inv sc1
	buffer_wbl2 sc1
	s_waitcnt lgkmcnt(0)
	s_waitcnt vmcnt(0)
	v_mbcnt_lo_u32_b32 v1, s6, 0
	v_mbcnt_hi_u32_b32 v1, s7, v1
	v_cmp_eq_u32_e32 vcc, 0, v1
	s_and_saveexec_b64 s[8:9], vcc
	s_cbranch_execz .LBB0_1094
	s_bcnt1_i32_b64 s6, s[6:7]
	v_mov_b32_e32 v2, s6
	v_readlane_b32 s6, v253, 14
	v_readlane_b32 s7, v253, 15
	s_nop 4
	global_atomic_add v2, v161, v2, s[6:7] sc0

; __device__ __forceinline__ unsigned xb_ld(unsigned* p)              { return __hip_atomic_load(p, __ATOMIC_RELAXED, __HIP_MEMORY_SCOPE_AGENT); }
; __device__ __forceinline__ unsigned xb_add(unsigned* p, unsigned v) { return __hip_atomic_fetch_add(p, v, __ATOMIC_RELAXED, __HIP_MEMORY_SCOPE_AGENT); }
; #define XB_SPIN(cond, bar) do { unsigned _sp = 0; while (cond) { __builtin_amdgcn_s_sleep(1); \
;     if ((++_sp & 255u) == 0u) { if (xb_ld(&(bar)[XB_TMO])) break; if (_sp > XB_SPIN_CAP) { atomicAdd(&(bar)[XB_TMO], 1u); break; } } } } while (0)
; __device__ __forceinline__ void xcd_barrier(const XcdBarrier& b, int xtid) {
;     ...
;             if (og + 1u == (tg + 1u) * nx) xb_add(&bar[XB_TOPGEN], 1u);
;             else XB_SPIN(xb_ld(&bar[XB_TOPGEN]) == tg, bar);
;             __builtin_amdgcn_fence(__ATOMIC_ACQUIRE, "agent");
;             xb_add(&bar[XB_XGEN(b.x)], 1u);
;             asm volatile("s_waitcnt vmcnt(0)" ::: "memory");
.LBB0_1108:
	s_or_b64 exec, exec, s[6:7]
	s_mov_b64 s[6:7], exec
	v_mbcnt_lo_u32_b32 v0, s6, 0
	v_mbcnt_hi_u32_b32 v0, s7, v0
	v_cmp_eq_u32_e32 vcc, 0, v0
	s_waitcnt vmcnt(0)
	s_nop 0
	s_and_saveexec_b64 s[8:9], vcc
	s_cbranch_execnz .LBB0_1109
	s_getpc_b64 s[98:99]

; __device__ __forceinline__ unsigned xb_add(unsigned* p, unsigned v) { return __hip_atomic_fetch_add(p, v, __ATOMIC_RELAXED, __HIP_MEMORY_SCOPE_AGENT); }
; __device__ __forceinline__ void xcd_barrier(const XcdBarrier& b, int xtid) {
;     ...
;             xb_add(&bar[XB_XGEN(b.x)], 1u);
;             asm volatile("s_waitcnt vmcnt(0)" ::: "memory");
.LBB0_1109:
	s_bcnt1_i32_b64 s6, s[6:7]
	v_mov_b32_e32 v0, s6
	s_nop 0
	s_getpc_b64 s[98:99]
